# K-loop phases: lgkmcnt wait moved past the phase barrier to its MFMA consumers as counted waits (fp16 and fp8 mainloops)
# speedup vs baseline: 1.0111x; 1.0111x over previous
; #define PG8_STAGE(bufoff, gbase, voff, h64) do { \
;         __builtin_amdgcn_global_load_lds((const unsigned*)((const char*)(gbase) + (voff)), (LAS unsigned*)(lds + (bufoff) + ldsw), 16, 0, 0); \
;         __builtin_amdgcn_global_load_lds((const unsigned*)((const char*)(gbase) + (h64) + (voff)), (LAS unsigned*)(lds + (bufoff) + ldsw + 8192), 16, 0, 0); } while (0)
; #define PG8_LDA(dst, b, h) do { _Pragma("unroll") for (int m = 0; m < 4; ++m) { dst[m].lo = *(const LAS f16x8*)(lds + PG8_SA(b, h) + aoff + m * 2048); dst[m].hi = *(const LAS f16x8*)(lds + PG8_SA(b, h) + aoff + m * 2048 + 1024); } } while (0)
; #define PG8_LDB(dst, b, h) do { _Pragma("unroll") for (int n = 0; n < 2; ++n) { dst[n].lo = *(const LAS f16x8*)(lds + PG8_SB(b, h) + boff + n * 2048); dst[n].hi = *(const LAS f16x8*)(lds + PG8_SB(b, h) + boff + n * 2048 + 1024); } } while (0)
; #define PG8_WAIT_V(n) asm volatile("s_waitcnt vmcnt(" #n ")" ::: "memory")
; #define PG8_WAIT_L(n) asm volatile("s_waitcnt lgkmcnt(" #n ")" ::: "memory")
; #define PG8_BAR __builtin_amdgcn_s_barrier()
; #define PG8_SCHED __builtin_amdgcn_sched_barrier(0)
; template <bool F8 = false, class Sched, class Epi>
; __device__ __forceinline__ void gemm_phase(LAS unsigned char* lds, const Sched& S, const Epi& E) {
;     ...
;         for (int t = 0; t < nt; t += 2) {
;             const bool last = (t == nt - 2);
;             const char* a1 = cA + (size_t)(t + 1) * kstep;
;             const char* a2 = last ? nA : cA + (size_t)(t + 2) * kstep; const char* b2 = last ? nB : cB + (size_t)(t + 2) * kstep;
;             const char* a3 = a2 + kstep; const char* b3 = b2 + kstep;
;             const unsigned vA2 = last ? nvA : cvA, vB2 = last ? nvB : cvB;
;             const size_t h2 = last ? nh64 : ch64, hs2 = last ? nhs : chs, bhs2 = last ? nbhs : cbhs;
;             PG8_LDB(B0, 0, 0); PG8_LDB(B1, 0, 1); PG8_SCHED; PG8_LDA(At, 0, 0); PG8_STAGE(PG8_SA(1, 1), a1 + chs, cvA, ch64);
;             PG8_WAIT_V(8); PG8_WAIT_L(0); PG8_BAR; PG8_MMA(0, 0, At, B0); PG8_MMA(0, 1, At, B1); PG8_BAR; PG8_SCHED;
;             PG8_LDA(At, 0, 1); PG8_STAGE(PG8_SB(0, 0), b2, vB2, h2); PG8_STAGE(PG8_SB(0, 1), b2 + bhs2, vB2, h2); PG8_STAGE(PG8_SA(0, 0), a2, vA2, h2);
;             PG8_WAIT_V(8); PG8_WAIT_L(0); PG8_BAR; PG8_MMA(1, 0, At, B0); PG8_MMA(1, 1, At, B1); PG8_BAR; PG8_SCHED;
.LBB0_73:
	s_add_u32 s24, s12, s8
	s_addc_u32 s25, s13, s9
	s_add_u32 s26, s24, 0x100
	s_addc_u32 s27, s25, 0
	s_add_u32 s36, s71, s8
	s_addc_u32 s68, s72, s9
	s_cmpk_eq_i32 s8, 0x300
	s_cselect_b64 vcc, -1, 0
	s_and_b64 s[24:25], vcc, exec
	s_cselect_b32 s25, s73, s27
	s_cselect_b32 s24, s74, s26
	s_cselect_b32 s27, s75, s68
	s_cselect_b32 s26, s80, s36
	s_add_i32 s36, 0, 0x10000
	s_add_i32 s68, 0, 0x14000
	v_add_u32_e32 v0, s36, v163
	v_add_u32_e32 v12, s68, v163
	ds_read_b128 v[16:19], v0
	ds_read_b128 v[20:23], v0 offset:1024
	ds_read_b128 v[24:27], v0 offset:2048
	ds_read_b128 v[28:31], v0 offset:3072
	ds_read_b128 v[0:3], v12
	ds_read_b128 v[4:7], v12 offset:1024
	ds_read_b128 v[8:11], v12 offset:2048
	ds_read_b128 v[12:15], v12 offset:3072
	v_cndmask_b32_e32 v32, v164, v166, vcc
	v_cndmask_b32_e32 v172, v162, v175, vcc
	v_lshl_add_u64 v[170:171], v[168:169], 0, s[8:9]
	v_lshl_add_u64 v[192:193], v[170:171], 0, s[58:59]
	s_add_i32 m0, s31, 0xc000
	ds_read_b128 v[176:179], v174
	ds_read_b128 v[180:183], v174 offset:1024
	ds_read_b128 v[184:187], v174 offset:2048
	ds_read_b128 v[188:191], v174 offset:3072
	ds_read_b128 v[198:201], v174 offset:4096
	ds_read_b128 v[202:205], v174 offset:5120
	ds_read_b128 v[206:209], v174 offset:6144
	ds_read_b128 v[210:213], v174 offset:7168
	global_load_lds_dwordx4 v[192:193], off
	v_lshl_add_u64 v[170:171], v[170:171], 0, s[76:77]
	s_add_i32 m0, s31, 0xe000
	s_nop 0
	global_load_lds_dwordx4 v[170:171], off
	s_waitcnt vmcnt(8)
	s_nop 0
	s_setprio 1
	s_barrier
	s_waitcnt lgkmcnt(0)
	v_mfma_scale_f32_16x16x128_f8f6f4 v[158:161], v[16:23], v[176:183], v[158:161], v220, v221 op_sel_hi:[0,0,0]
	v_mfma_scale_f32_16x16x128_f8f6f4 v[154:157], v[24:31], v[176:183], v[154:157], v220, v221 op_sel_hi:[0,0,0]
	v_mfma_scale_f32_16x16x128_f8f6f4 v[150:153], v[16:23], v[184:191], v[150:153], v220, v221 op_sel_hi:[0,0,0]
	v_mfma_scale_f32_16x16x128_f8f6f4 v[146:149], v[24:31], v[184:191], v[146:149], v220, v221 op_sel_hi:[0,0,0]
	v_mfma_scale_f32_16x16x128_f8f6f4 v[142:145], v[16:23], v[198:205], v[142:145], v220, v221 op_sel_hi:[0,0,0]
	v_mfma_scale_f32_16x16x128_f8f6f4 v[138:141], v[24:31], v[198:205], v[138:141], v220, v221 op_sel_hi:[0,0,0]
	v_mfma_scale_f32_16x16x128_f8f6f4 v[134:137], v[16:23], v[206:213], v[134:137], v220, v221 op_sel_hi:[0,0,0]
	v_mfma_scale_f32_16x16x128_f8f6f4 v[130:133], v[24:31], v[206:213], v[130:133], v220, v221 op_sel_hi:[0,0,0]
	v_mfma_scale_f32_16x16x128_f8f6f4 v[126:129], v[0:7], v[176:183], v[126:129], v220, v221 op_sel_hi:[0,0,0]
	v_mfma_scale_f32_16x16x128_f8f6f4 v[122:125], v[8:15], v[176:183], v[122:125], v220, v221 op_sel_hi:[0,0,0]
	v_mfma_scale_f32_16x16x128_f8f6f4 v[118:121], v[0:7], v[184:191], v[118:121], v220, v221 op_sel_hi:[0,0,0]
	v_mfma_scale_f32_16x16x128_f8f6f4 v[114:117], v[8:15], v[184:191], v[114:117], v220, v221 op_sel_hi:[0,0,0]
	v_mfma_scale_f32_16x16x128_f8f6f4 v[110:113], v[0:7], v[198:205], v[110:113], v220, v221 op_sel_hi:[0,0,0]
	v_mfma_scale_f32_16x16x128_f8f6f4 v[106:109], v[8:15], v[198:205], v[106:109], v220, v221 op_sel_hi:[0,0,0]
	v_mfma_scale_f32_16x16x128_f8f6f4 v[102:105], v[0:7], v[206:213], v[102:105], v220, v221 op_sel_hi:[0,0,0]
	v_mfma_scale_f32_16x16x128_f8f6f4 v[98:101], v[8:15], v[206:213], v[98:101], v220, v221 op_sel_hi:[0,0,0]
	s_barrier
	s_setprio 0
	v_mov_b32_e32 v173, v33
	s_add_i32 s36, s36, s49
	v_lshl_add_u64 v[170:171], s[26:27], 0, v[172:173]
	s_mov_b32 m0, s36
	ds_read_b128 v[176:179], v174 offset:16384
	ds_read_b128 v[180:183], v174 offset:17408
	ds_read_b128 v[184:187], v174 offset:18432
	ds_read_b128 v[188:191], v174 offset:19456
	ds_read_b128 v[198:201], v174 offset:20480
	ds_read_b128 v[202:205], v174 offset:21504
	ds_read_b128 v[206:209], v174 offset:22528
	ds_read_b128 v[210:213], v174 offset:23552
	global_load_lds_dwordx4 v172, s[26:27]
	v_lshl_add_u64 v[172:173], v[170:171], 0, s[38:39]
	s_add_i32 m0, s36, 0x2000
	s_add_i32 s26, s68, s49
	global_load_lds_dwordx4 v[172:173], off
	v_lshl_add_u64 v[172:173], v[170:171], 0, s[60:61]
	s_mov_b32 m0, s26
	s_nop 0
	global_load_lds_dwordx4 v[172:173], off
	v_lshl_add_u64 v[172:173], v[170:171], 0, s[0:1]
	s_add_i32 m0, s26, 0x2000
	s_nop 0
	global_load_lds_dwordx4 v[172:173], off
	v_lshl_add_u64 v[172:173], s[24:25], 0, v[32:33]
	s_mov_b32 m0, s31
	v_lshl_add_u64 v[192:193], v[172:173], 0, s[38:39]
	global_load_lds_dwordx4 v[172:173], off
	s_mov_b32 m0, s34
	s_nop 0
	global_load_lds_dwordx4 v[192:193], off
	s_waitcnt vmcnt(8)
	s_nop 0
	s_setprio 1
	s_barrier
	s_waitcnt lgkmcnt(6)
	v_mfma_scale_f32_16x16x128_f8f6f4 v[94:97], v[16:23], v[176:183], v[94:97], v220, v221 op_sel_hi:[0,0,0]
	v_mfma_scale_f32_16x16x128_f8f6f4 v[90:93], v[24:31], v[176:183], v[90:93], v220, v221 op_sel_hi:[0,0,0]
	s_waitcnt lgkmcnt(4)
	v_mfma_scale_f32_16x16x128_f8f6f4 v[86:89], v[16:23], v[184:191], v[86:89], v220, v221 op_sel_hi:[0,0,0]
	v_mfma_scale_f32_16x16x128_f8f6f4 v[82:85], v[24:31], v[184:191], v[82:85], v220, v221 op_sel_hi:[0,0,0]
	s_waitcnt lgkmcnt(2)
	v_mfma_scale_f32_16x16x128_f8f6f4 v[78:81], v[16:23], v[198:205], v[78:81], v220, v221 op_sel_hi:[0,0,0]
	v_mfma_scale_f32_16x16x128_f8f6f4 v[74:77], v[24:31], v[198:205], v[74:77], v220, v221 op_sel_hi:[0,0,0]
	s_waitcnt lgkmcnt(0)
	v_mfma_scale_f32_16x16x128_f8f6f4 v[70:73], v[16:23], v[206:213], v[70:73], v220, v221 op_sel_hi:[0,0,0]
	v_mfma_scale_f32_16x16x128_f8f6f4 v[66:69], v[24:31], v[206:213], v[66:69], v220, v221 op_sel_hi:[0,0,0]
	v_mfma_scale_f32_16x16x128_f8f6f4 v[62:65], v[0:7], v[176:183], v[62:65], v220, v221 op_sel_hi:[0,0,0]
	v_mfma_scale_f32_16x16x128_f8f6f4 v[58:61], v[8:15], v[176:183], v[58:61], v220, v221 op_sel_hi:[0,0,0]
	v_mfma_scale_f32_16x16x128_f8f6f4 v[54:57], v[0:7], v[184:191], v[54:57], v220, v221 op_sel_hi:[0,0,0]
	v_mfma_scale_f32_16x16x128_f8f6f4 v[50:53], v[8:15], v[184:191], v[50:53], v220, v221 op_sel_hi:[0,0,0]
	v_mfma_scale_f32_16x16x128_f8f6f4 v[46:49], v[0:7], v[198:205], v[46:49], v220, v221 op_sel_hi:[0,0,0]
	v_mfma_scale_f32_16x16x128_f8f6f4 v[42:45], v[8:15], v[198:205], v[42:45], v220, v221 op_sel_hi:[0,0,0]
	v_mfma_scale_f32_16x16x128_f8f6f4 v[38:41], v[0:7], v[206:213], v[38:41], v220, v221 op_sel_hi:[0,0,0]
	v_mfma_scale_f32_16x16x128_f8f6f4 v[34:37], v[8:15], v[206:213], v[34:37], v220, v221 op_sel_hi:[0,0,0]
	s_barrier
; #define PG8_STAGE(bufoff, gbase, voff, h64) do { \
;         __builtin_amdgcn_global_load_lds((const unsigned*)((const char*)(gbase) + (voff)), (LAS unsigned*)(lds + (bufoff) + ldsw), 16, 0, 0); \
;         __builtin_amdgcn_global_load_lds((const unsigned*)((const char*)(gbase) + (h64) + (voff)), (LAS unsigned*)(lds + (bufoff) + ldsw + 8192), 16, 0, 0); } while (0)
; #define PG8_LDA(dst, b, h) do { _Pragma("unroll") for (int m = 0; m < 4; ++m) { dst[m].lo = *(const LAS f16x8*)(lds + PG8_SA(b, h) + aoff + m * 2048); dst[m].hi = *(const LAS f16x8*)(lds + PG8_SA(b, h) + aoff + m * 2048 + 1024); } } while (0)
; #define PG8_LDB(dst, b, h) do { _Pragma("unroll") for (int n = 0; n < 2; ++n) { dst[n].lo = *(const LAS f16x8*)(lds + PG8_SB(b, h) + boff + n * 2048); dst[n].hi = *(const LAS f16x8*)(lds + PG8_SB(b, h) + boff + n * 2048 + 1024); } } while (0)
; #define PG8_WAIT_V(n) asm volatile("s_waitcnt vmcnt(" #n ")" ::: "memory")
; #define PG8_WAIT_L(n) asm volatile("s_waitcnt lgkmcnt(" #n ")" ::: "memory")
; #define PG8_BAR __builtin_amdgcn_s_barrier()
; #define PG8_SCHED __builtin_amdgcn_sched_barrier(0)
; template <bool F8 = false, class Sched, class Epi>
; __device__ __forceinline__ void gemm_phase(LAS unsigned char* lds, const Sched& S, const Epi& E) {
;     ...
;             PG8_LDB(B0, 1, 0); PG8_LDB(B1, 1, 1); PG8_SCHED; PG8_LDA(At, 1, 0); PG8_STAGE(PG8_SA(0, 1), a2 + hs2, vA2, h2);
;             PG8_WAIT_V(8); PG8_WAIT_L(0); PG8_BAR; PG8_MMA(0, 0, At, B0); PG8_MMA(0, 1, At, B1); PG8_BAR; PG8_SCHED;
;             PG8_LDA(At, 1, 1); PG8_STAGE(PG8_SB(1, 0), b3, vB2, h2); PG8_STAGE(PG8_SB(1, 1), b3 + bhs2, vB2, h2); PG8_STAGE(PG8_SA(1, 0), a3, vA2, h2);
;             PG8_WAIT_V(8); PG8_WAIT_L(0); PG8_BAR; PG8_MMA(1, 0, At, B0); PG8_MMA(1, 1, At, B1); PG8_BAR; PG8_SCHED;
;         }
;         if (wr == 0) PG8_BAR;
	s_setprio 0
	s_add_i32 s24, 0, 0x18000
	s_add_i32 s25, 0, 0x1c000
	v_add_u32_e32 v12, s24, v163
	v_add_u32_e32 v28, s25, v163
	ds_read_b128 v[0:3], v12
	ds_read_b128 v[4:7], v12 offset:1024
	ds_read_b128 v[8:11], v12 offset:2048
	ds_read_b128 v[12:15], v12 offset:3072
	ds_read_b128 v[16:19], v28
	ds_read_b128 v[20:23], v28 offset:1024
	ds_read_b128 v[24:27], v28 offset:2048
	ds_read_b128 v[28:31], v28 offset:3072
	s_mov_b32 m0, s35
	v_lshl_add_u64 v[192:193], v[172:173], 0, s[60:61]
	ds_read_b128 v[176:179], v174 offset:32768
	ds_read_b128 v[180:183], v174 offset:33792
	ds_read_b128 v[184:187], v174 offset:34816
	ds_read_b128 v[188:191], v174 offset:35840
	ds_read_b128 v[198:201], v174 offset:36864
	ds_read_b128 v[202:205], v174 offset:37888
	ds_read_b128 v[206:209], v174 offset:38912
	ds_read_b128 v[210:213], v174 offset:39936
	global_load_lds_dwordx4 v[192:193], off
	v_lshl_add_u64 v[192:193], v[172:173], 0, s[0:1]
	s_mov_b32 m0, s37
	s_nop 0
	global_load_lds_dwordx4 v[192:193], off
	s_waitcnt vmcnt(8)
	s_nop 0
	s_setprio 1
	s_barrier
	s_waitcnt lgkmcnt(6)
	v_mfma_scale_f32_16x16x128_f8f6f4 v[158:161], v[0:7], v[176:183], v[158:161], v220, v221 op_sel_hi:[0,0,0]
	v_mfma_scale_f32_16x16x128_f8f6f4 v[154:157], v[8:15], v[176:183], v[154:157], v220, v221 op_sel_hi:[0,0,0]
	s_waitcnt lgkmcnt(4)
	v_mfma_scale_f32_16x16x128_f8f6f4 v[150:153], v[0:7], v[184:191], v[150:153], v220, v221 op_sel_hi:[0,0,0]
	v_mfma_scale_f32_16x16x128_f8f6f4 v[146:149], v[8:15], v[184:191], v[146:149], v220, v221 op_sel_hi:[0,0,0]
	s_waitcnt lgkmcnt(2)
	v_mfma_scale_f32_16x16x128_f8f6f4 v[142:145], v[0:7], v[198:205], v[142:145], v220, v221 op_sel_hi:[0,0,0]
	v_mfma_scale_f32_16x16x128_f8f6f4 v[138:141], v[8:15], v[198:205], v[138:141], v220, v221 op_sel_hi:[0,0,0]
	s_waitcnt lgkmcnt(0)
	v_mfma_scale_f32_16x16x128_f8f6f4 v[134:137], v[0:7], v[206:213], v[134:137], v220, v221 op_sel_hi:[0,0,0]
	v_mfma_scale_f32_16x16x128_f8f6f4 v[130:133], v[8:15], v[206:213], v[130:133], v220, v221 op_sel_hi:[0,0,0]
	v_mfma_scale_f32_16x16x128_f8f6f4 v[126:129], v[16:23], v[176:183], v[126:129], v220, v221 op_sel_hi:[0,0,0]
	v_mfma_scale_f32_16x16x128_f8f6f4 v[122:125], v[24:31], v[176:183], v[122:125], v220, v221 op_sel_hi:[0,0,0]
	v_mfma_scale_f32_16x16x128_f8f6f4 v[118:121], v[16:23], v[184:191], v[118:121], v220, v221 op_sel_hi:[0,0,0]
	v_mfma_scale_f32_16x16x128_f8f6f4 v[114:117], v[24:31], v[184:191], v[114:117], v220, v221 op_sel_hi:[0,0,0]
	v_mfma_scale_f32_16x16x128_f8f6f4 v[110:113], v[16:23], v[198:205], v[110:113], v220, v221 op_sel_hi:[0,0,0]
	v_mfma_scale_f32_16x16x128_f8f6f4 v[106:109], v[24:31], v[198:205], v[106:109], v220, v221 op_sel_hi:[0,0,0]
	v_mfma_scale_f32_16x16x128_f8f6f4 v[102:105], v[16:23], v[206:213], v[102:105], v220, v221 op_sel_hi:[0,0,0]
	v_mfma_scale_f32_16x16x128_f8f6f4 v[98:101], v[24:31], v[206:213], v[98:101], v220, v221 op_sel_hi:[0,0,0]
	s_barrier
	s_setprio 0
	s_add_i32 s24, s24, s49
	v_lshl_add_u64 v[192:193], v[170:171], 0, s[40:41]
	s_mov_b32 m0, s24
	ds_read_b128 v[176:179], v174 offset:49152
	ds_read_b128 v[180:183], v174 offset:50176
	ds_read_b128 v[184:187], v174 offset:51200
	ds_read_b128 v[188:191], v174 offset:52224
	ds_read_b128 v[198:201], v174 offset:53248
	ds_read_b128 v[202:205], v174 offset:54272
	ds_read_b128 v[206:209], v174 offset:55296
	ds_read_b128 v[210:213], v174 offset:56320
	global_load_lds_dwordx4 v[192:193], off
	v_lshl_add_u64 v[192:193], v[170:171], 0, s[56:57]
	s_add_i32 m0, s24, 0x2000
	s_add_i32 s24, s25, s49
	global_load_lds_dwordx4 v[192:193], off
	v_lshl_add_u64 v[192:193], v[170:171], 0, s[58:59]
	s_mov_b32 m0, s24
	v_lshl_add_u64 v[170:171], v[170:171], 0, s[76:77]
	global_load_lds_dwordx4 v[192:193], off
	s_add_i32 m0, s24, 0x2000
	s_nop 0
	global_load_lds_dwordx4 v[170:171], off
	v_lshl_add_u64 v[170:171], v[172:173], 0, s[40:41]
	s_mov_b32 m0, s42
	s_nop 0
	global_load_lds_dwordx4 v[170:171], off
	v_lshl_add_u64 v[170:171], v[172:173], 0, s[56:57]
	s_mov_b32 m0, s43
	s_nop 0
	global_load_lds_dwordx4 v[170:171], off
	s_waitcnt vmcnt(8)
	s_nop 0
	s_setprio 1
	s_barrier
	s_waitcnt lgkmcnt(6)
	v_mfma_scale_f32_16x16x128_f8f6f4 v[94:97], v[0:7], v[176:183], v[94:97], v220, v221 op_sel_hi:[0,0,0]
	v_mfma_scale_f32_16x16x128_f8f6f4 v[90:93], v[8:15], v[176:183], v[90:93], v220, v221 op_sel_hi:[0,0,0]
	s_waitcnt lgkmcnt(4)
	v_mfma_scale_f32_16x16x128_f8f6f4 v[86:89], v[0:7], v[184:191], v[86:89], v220, v221 op_sel_hi:[0,0,0]
	v_mfma_scale_f32_16x16x128_f8f6f4 v[82:85], v[8:15], v[184:191], v[82:85], v220, v221 op_sel_hi:[0,0,0]
	s_waitcnt lgkmcnt(2)
	v_mfma_scale_f32_16x16x128_f8f6f4 v[78:81], v[0:7], v[198:205], v[78:81], v220, v221 op_sel_hi:[0,0,0]
	v_mfma_scale_f32_16x16x128_f8f6f4 v[74:77], v[8:15], v[198:205], v[74:77], v220, v221 op_sel_hi:[0,0,0]
	s_waitcnt lgkmcnt(0)
	v_mfma_scale_f32_16x16x128_f8f6f4 v[70:73], v[0:7], v[206:213], v[70:73], v220, v221 op_sel_hi:[0,0,0]
	v_mfma_scale_f32_16x16x128_f8f6f4 v[66:69], v[8:15], v[206:213], v[66:69], v220, v221 op_sel_hi:[0,0,0]
	v_mfma_scale_f32_16x16x128_f8f6f4 v[62:65], v[16:23], v[176:183], v[62:65], v220, v221 op_sel_hi:[0,0,0]
	v_mfma_scale_f32_16x16x128_f8f6f4 v[58:61], v[24:31], v[176:183], v[58:61], v220, v221 op_sel_hi:[0,0,0]
	v_mfma_scale_f32_16x16x128_f8f6f4 v[54:57], v[16:23], v[184:191], v[54:57], v220, v221 op_sel_hi:[0,0,0]
	v_mfma_scale_f32_16x16x128_f8f6f4 v[50:53], v[24:31], v[184:191], v[50:53], v220, v221 op_sel_hi:[0,0,0]
	v_mfma_scale_f32_16x16x128_f8f6f4 v[46:49], v[16:23], v[198:205], v[46:49], v220, v221 op_sel_hi:[0,0,0]
	v_mfma_scale_f32_16x16x128_f8f6f4 v[42:45], v[24:31], v[198:205], v[42:45], v220, v221 op_sel_hi:[0,0,0]
	v_mfma_scale_f32_16x16x128_f8f6f4 v[38:41], v[16:23], v[206:213], v[38:41], v220, v221 op_sel_hi:[0,0,0]
	v_mfma_scale_f32_16x16x128_f8f6f4 v[34:37], v[24:31], v[206:213], v[34:37], v220, v221 op_sel_hi:[0,0,0]
	s_barrier
	s_setprio 0
	s_add_i32 s81, s81, 2
	s_add_u32 s8, s8, 0x100
	s_addc_u32 s9, s9, 0
	s_cmp_gt_u32 s81, 5
	s_cbranch_scc0 .LBB0_73
	v_readlane_b32 s8, v251, 12
	v_readlane_b32 s9, v251, 13
	s_and_b64 vcc, exec, s[8:9]
	s_cbranch_vccz .LBB0_76
	s_barrier

; #define PG8_STAGE(bufoff, gbase, voff, h64) do { \
;         __builtin_amdgcn_global_load_lds((const unsigned*)((const char*)(gbase) + (voff)), (LAS unsigned*)(lds + (bufoff) + ldsw), 16, 0, 0); \
;         __builtin_amdgcn_global_load_lds((const unsigned*)((const char*)(gbase) + (h64) + (voff)), (LAS unsigned*)(lds + (bufoff) + ldsw + 8192), 16, 0, 0); } while (0)
; #define PG8_LDA(dst, b, h) do { _Pragma("unroll") for (int m = 0; m < 4; ++m) { dst[m].lo = *(const LAS f16x8*)(lds + PG8_SA(b, h) + aoff + m * 2048); dst[m].hi = *(const LAS f16x8*)(lds + PG8_SA(b, h) + aoff + m * 2048 + 1024); } } while (0)
; #define PG8_LDB(dst, b, h) do { _Pragma("unroll") for (int n = 0; n < 2; ++n) { dst[n].lo = *(const LAS f16x8*)(lds + PG8_SB(b, h) + boff + n * 2048); dst[n].hi = *(const LAS f16x8*)(lds + PG8_SB(b, h) + boff + n * 2048 + 1024); } } while (0)
; #define PG8_WAIT_V(n) asm volatile("s_waitcnt vmcnt(" #n ")" ::: "memory")
; #define PG8_WAIT_L(n) asm volatile("s_waitcnt lgkmcnt(" #n ")" ::: "memory")
; #define PG8_BAR __builtin_amdgcn_s_barrier()
; #define PG8_SCHED __builtin_amdgcn_sched_barrier(0)
; template <bool F8 = false, class Sched, class Epi>
; __device__ __forceinline__ void gemm_phase(LAS unsigned char* lds, const Sched& S, const Epi& E) {
;     ...
;             const bool last = (t == nt - 2);
;             const char* a1 = cA + (size_t)(t + 1) * kstep;
;             const char* a2 = last ? nA : cA + (size_t)(t + 2) * kstep; const char* b2 = last ? nB : cB + (size_t)(t + 2) * kstep;
;             const char* a3 = a2 + kstep; const char* b3 = b2 + kstep;
;             const unsigned vA2 = last ? nvA : cvA, vB2 = last ? nvB : cvB;
;             const size_t h2 = last ? nh64 : ch64, hs2 = last ? nhs : chs, bhs2 = last ? nbhs : cbhs;
;             PG8_LDB(B0, 0, 0); PG8_LDB(B1, 0, 1); PG8_SCHED; PG8_LDA(At, 0, 0); PG8_STAGE(PG8_SA(1, 1), a1 + chs, cvA, ch64);
;             PG8_WAIT_V(8); PG8_WAIT_L(0); PG8_BAR; PG8_MMA(0, 0, At, B0); PG8_MMA(0, 1, At, B1); PG8_BAR; PG8_SCHED;
;             PG8_LDA(At, 0, 1); PG8_STAGE(PG8_SB(0, 0), b2, vB2, h2); PG8_STAGE(PG8_SB(0, 1), b2 + bhs2, vB2, h2); PG8_STAGE(PG8_SA(0, 0), a2, vA2, h2);
;             PG8_WAIT_V(8); PG8_WAIT_L(0); PG8_BAR; PG8_MMA(1, 0, At, B0); PG8_MMA(1, 1, At, B1); PG8_BAR; PG8_SCHED;
.Lk16_sel:
	s_add_i32 s79, s79, 2
	s_add_u32 vcc_lo, s14, s10
	s_addc_u32 vcc_hi, s15, s11
	s_add_u32 vcc_lo, vcc_lo, 0x100
	s_addc_u32 vcc_hi, vcc_hi, 0
	s_and_b64 s[86:87], exec, s[86:87]
	s_cselect_b32 vcc_hi, s29, vcc_hi
	s_cselect_b32 vcc_lo, s96, vcc_lo
	s_add_i32 s86, 0, 0x10000
	s_add_i32 s45, 0, 0x14000
	s_waitcnt vmcnt(8)
	s_nop 0
	s_setprio 1
	s_barrier
	s_waitcnt lgkmcnt(0)
	v_mfma_f32_16x16x32_f16 v[128:131], v[138:141], v[170:173], v[128:131]
	v_mfma_f32_16x16x32_f16 v[124:127], v[146:149], v[170:173], v[124:127]
	v_mfma_f32_16x16x32_f16 v[112:115], v[138:141], v[178:181], v[112:115]
	v_mfma_f32_16x16x32_f16 v[108:111], v[146:149], v[178:181], v[108:111]
	v_mfma_f32_16x16x32_f16 v[96:99], v[138:141], v[198:201], v[96:99]
	v_mfma_f32_16x16x32_f16 v[92:95], v[146:149], v[198:201], v[92:95]
	v_mfma_f32_16x16x32_f16 v[80:83], v[138:141], v[208:211], v[80:83]
	v_mfma_f32_16x16x32_f16 v[76:79], v[146:149], v[208:211], v[76:79]
	v_mfma_f32_16x16x32_f16 v[128:131], v[142:145], v[174:177], v[128:131]
	v_mfma_f32_16x16x32_f16 v[124:127], v[150:153], v[174:177], v[124:127]
	v_mfma_f32_16x16x32_f16 v[112:115], v[142:145], v[190:193], v[112:115]
	v_mfma_f32_16x16x32_f16 v[108:111], v[150:153], v[190:193], v[108:111]
	v_mfma_f32_16x16x32_f16 v[96:99], v[142:145], v[204:207], v[96:99]
	v_mfma_f32_16x16x32_f16 v[92:95], v[150:153], v[204:207], v[92:95]
	v_mfma_f32_16x16x32_f16 v[80:83], v[142:145], v[212:215], v[80:83]
	v_mfma_f32_16x16x32_f16 v[76:79], v[150:153], v[212:215], v[76:79]
	v_mfma_f32_16x16x32_f16 v[120:123], v[154:157], v[170:173], v[120:123]
	v_mfma_f32_16x16x32_f16 v[116:119], v[162:165], v[170:173], v[116:119]
	v_mfma_f32_16x16x32_f16 v[104:107], v[154:157], v[178:181], v[104:107]
	v_mfma_f32_16x16x32_f16 v[100:103], v[162:165], v[178:181], v[100:103]
	v_mfma_f32_16x16x32_f16 v[88:91], v[154:157], v[198:201], v[88:91]
	v_mfma_f32_16x16x32_f16 v[84:87], v[162:165], v[198:201], v[84:87]
	v_mfma_f32_16x16x32_f16 v[72:75], v[154:157], v[208:211], v[72:75]
	v_mfma_f32_16x16x32_f16 v[68:71], v[162:165], v[208:211], v[68:71]
	v_mfma_f32_16x16x32_f16 v[120:123], v[158:161], v[174:177], v[120:123]
	v_mfma_f32_16x16x32_f16 v[116:119], v[166:169], v[174:177], v[116:119]
	v_mfma_f32_16x16x32_f16 v[104:107], v[158:161], v[190:193], v[104:107]
	v_mfma_f32_16x16x32_f16 v[100:103], v[166:169], v[190:193], v[100:103]
	v_mfma_f32_16x16x32_f16 v[88:91], v[158:161], v[204:207], v[88:91]
	v_mfma_f32_16x16x32_f16 v[84:87], v[166:169], v[204:207], v[84:87]
	v_mfma_f32_16x16x32_f16 v[72:75], v[158:161], v[212:215], v[72:75]
	v_mfma_f32_16x16x32_f16 v[68:71], v[166:169], v[212:215], v[68:71]
	s_barrier
	s_setprio 0
	s_add_i32 s65, s86, s49
	s_mov_b32 m0, s65
	s_add_u32 s86, s6, s12
	ds_read_b128 v[170:173], v202 offset:16384
	ds_read_b128 v[174:177], v202 offset:17408
	ds_read_b128 v[178:181], v202 offset:18432
	ds_read_b128 v[190:193], v202 offset:19456
	ds_read_b128 v[198:201], v202 offset:20480
	ds_read_b128 v[204:207], v202 offset:21504
	ds_read_b128 v[208:211], v202 offset:22528
	ds_read_b128 v[212:215], v202 offset:23552
	global_load_lds_dwordx4 v32, s[6:7]
	s_addc_u32 s87, s7, s13
	s_add_i32 m0, s65, 0x2000
	v_lshl_add_u64 v[182:183], s[6:7], 0, v[32:33]
	s_add_u32 s6, s6, s8
	s_addc_u32 s7, s7, s9
	s_add_i32 s8, s45, s49
	global_load_lds_dwordx4 v32, s[86:87]
	s_mov_b32 m0, s8
	v_lshl_add_u64 v[216:217], s[6:7], 0, v[32:33]
	global_load_lds_dwordx4 v32, s[6:7]
	s_add_u32 s6, s6, s12
	s_addc_u32 s7, s7, s13
	s_add_i32 m0, s8, 0x2000
	v_lshl_add_u64 v[234:235], s[6:7], 0, v[32:33]
	global_load_lds_dwordx4 v32, s[6:7]
	s_add_u32 s6, vcc_lo, s12
	v_lshl_add_u64 v[236:237], vcc, 0, v[136:137]
	s_mov_b32 m0, s71
	s_addc_u32 s7, vcc_hi, s13
	global_load_lds_dwordx4 v[236:237], off
	v_lshl_add_u64 v[238:239], s[6:7], 0, v[136:137]
	s_mov_b32 m0, s82
	v_lshl_add_u64 v[194:195], s[86:87], 0, v[32:33]
	global_load_lds_dwordx4 v[238:239], off
	s_waitcnt vmcnt(8)
	s_nop 0
	s_setprio 1
	s_barrier
	s_waitcnt lgkmcnt(7)
	v_mfma_f32_16x16x32_f16 v[64:67], v[138:141], v[170:173], v[64:67]
	v_mfma_f32_16x16x32_f16 v[60:63], v[146:149], v[170:173], v[60:63]
	s_waitcnt lgkmcnt(5)
	v_mfma_f32_16x16x32_f16 v[48:51], v[138:141], v[178:181], v[48:51]
	v_mfma_f32_16x16x32_f16 v[44:47], v[146:149], v[178:181], v[44:47]
	s_waitcnt lgkmcnt(3)
	v_mfma_f32_16x16x32_f16 v[28:31], v[138:141], v[198:201], v[28:31]
	v_mfma_f32_16x16x32_f16 v[24:27], v[146:149], v[198:201], v[24:27]
	s_waitcnt lgkmcnt(1)
	v_mfma_f32_16x16x32_f16 v[12:15], v[138:141], v[208:211], v[12:15]
	v_mfma_f32_16x16x32_f16 v[8:11], v[146:149], v[208:211], v[8:11]
	v_mfma_f32_16x16x32_f16 v[64:67], v[142:145], v[174:177], v[64:67]
	v_mfma_f32_16x16x32_f16 v[60:63], v[150:153], v[174:177], v[60:63]
	v_mfma_f32_16x16x32_f16 v[48:51], v[142:145], v[190:193], v[48:51]
	v_mfma_f32_16x16x32_f16 v[44:47], v[150:153], v[190:193], v[44:47]
	v_mfma_f32_16x16x32_f16 v[28:31], v[142:145], v[204:207], v[28:31]
	v_mfma_f32_16x16x32_f16 v[24:27], v[150:153], v[204:207], v[24:27]
	s_waitcnt lgkmcnt(0)
	v_mfma_f32_16x16x32_f16 v[12:15], v[142:145], v[212:215], v[12:15]
	v_mfma_f32_16x16x32_f16 v[8:11], v[150:153], v[212:215], v[8:11]
	v_mfma_f32_16x16x32_f16 v[56:59], v[154:157], v[170:173], v[56:59]
	v_mfma_f32_16x16x32_f16 v[52:55], v[162:165], v[170:173], v[52:55]
	v_mfma_f32_16x16x32_f16 v[40:43], v[154:157], v[178:181], v[40:43]
	v_mfma_f32_16x16x32_f16 v[36:39], v[162:165], v[178:181], v[36:39]
	v_mfma_f32_16x16x32_f16 v[20:23], v[154:157], v[198:201], v[20:23]
	v_mfma_f32_16x16x32_f16 v[16:19], v[162:165], v[198:201], v[16:19]
	v_mfma_f32_16x16x32_f16 v[4:7], v[154:157], v[208:211], v[4:7]
	v_mfma_f32_16x16x32_f16 v[0:3], v[162:165], v[208:211], v[0:3]
	v_mfma_f32_16x16x32_f16 v[56:59], v[158:161], v[174:177], v[56:59]
	v_mfma_f32_16x16x32_f16 v[52:55], v[166:169], v[174:177], v[52:55]
	v_mfma_f32_16x16x32_f16 v[40:43], v[158:161], v[190:193], v[40:43]
	v_mfma_f32_16x16x32_f16 v[36:39], v[166:169], v[190:193], v[36:39]
	v_mfma_f32_16x16x32_f16 v[20:23], v[158:161], v[204:207], v[20:23]
	v_mfma_f32_16x16x32_f16 v[16:19], v[166:169], v[204:207], v[16:19]
	v_mfma_f32_16x16x32_f16 v[4:7], v[158:161], v[212:215], v[4:7]
	v_mfma_f32_16x16x32_f16 v[0:3], v[166:169], v[212:215], v[0:3]
	s_barrier
; #define PG8_STAGE(bufoff, gbase, voff, h64) do { \
;         __builtin_amdgcn_global_load_lds((const unsigned*)((const char*)(gbase) + (voff)), (LAS unsigned*)(lds + (bufoff) + ldsw), 16, 0, 0); \
;         __builtin_amdgcn_global_load_lds((const unsigned*)((const char*)(gbase) + (h64) + (voff)), (LAS unsigned*)(lds + (bufoff) + ldsw + 8192), 16, 0, 0); } while (0)
; #define PG8_LDA(dst, b, h) do { _Pragma("unroll") for (int m = 0; m < 4; ++m) { dst[m].lo = *(const LAS f16x8*)(lds + PG8_SA(b, h) + aoff + m * 2048); dst[m].hi = *(const LAS f16x8*)(lds + PG8_SA(b, h) + aoff + m * 2048 + 1024); } } while (0)
; #define PG8_LDB(dst, b, h) do { _Pragma("unroll") for (int n = 0; n < 2; ++n) { dst[n].lo = *(const LAS f16x8*)(lds + PG8_SB(b, h) + boff + n * 2048); dst[n].hi = *(const LAS f16x8*)(lds + PG8_SB(b, h) + boff + n * 2048 + 1024); } } while (0)
; #define PG8_WAIT_V(n) asm volatile("s_waitcnt vmcnt(" #n ")" ::: "memory")
; #define PG8_WAIT_L(n) asm volatile("s_waitcnt lgkmcnt(" #n ")" ::: "memory")
; #define PG8_BAR __builtin_amdgcn_s_barrier()
; #define PG8_SCHED __builtin_amdgcn_sched_barrier(0)
; template <bool F8 = false, class Sched, class Epi>
; __device__ __forceinline__ void gemm_phase(LAS unsigned char* lds, const Sched& S, const Epi& E) {
;     ...
;             PG8_LDB(B0, 1, 0); PG8_LDB(B1, 1, 1); PG8_SCHED; PG8_LDA(At, 1, 0); PG8_STAGE(PG8_SA(0, 1), a2 + hs2, vA2, h2);
;             PG8_WAIT_V(8); PG8_WAIT_L(0); PG8_BAR; PG8_MMA(0, 0, At, B0); PG8_MMA(0, 1, At, B1); PG8_BAR; PG8_SCHED;
	s_setprio 0
	s_add_i32 s8, 0, 0x18000
	v_add_u32_e32 v32, s8, v187
	s_add_i32 s9, 0, 0x1c000
	ds_read_b128 v[138:141], v32
	ds_read_b128 v[142:145], v32 offset:1024
	ds_read_b128 v[146:149], v32 offset:2048
	ds_read_b128 v[150:153], v32 offset:3072
	v_add_u32_e32 v32, s9, v187
	ds_read_b128 v[154:157], v32
	ds_read_b128 v[158:161], v32 offset:1024
	ds_read_b128 v[162:165], v32 offset:2048
	ds_read_b128 v[166:169], v32 offset:3072
	s_add_u32 s6, vcc_lo, s84
	s_addc_u32 s7, vcc_hi, s85
	v_lshl_add_u64 v[240:241], s[6:7], 0, v[136:137]
	s_add_u32 s6, s6, s12
	s_mov_b32 m0, s83
	s_addc_u32 s7, s7, s13
	ds_read_b128 v[170:173], v202 offset:32768
	ds_read_b128 v[174:177], v202 offset:33792
	ds_read_b128 v[178:181], v202 offset:34816
	ds_read_b128 v[190:193], v202 offset:35840
	ds_read_b128 v[198:201], v202 offset:36864
	ds_read_b128 v[204:207], v202 offset:37888
	ds_read_b128 v[208:211], v202 offset:38912
	ds_read_b128 v[212:215], v202 offset:39936
	global_load_lds_dwordx4 v[240:241], off
	v_lshl_add_u64 v[136:137], s[6:7], 0, v[136:137]
	s_mov_b32 m0, s44
	s_nop 0
	global_load_lds_dwordx4 v[136:137], off
	s_waitcnt vmcnt(8)
	s_nop 0
	s_setprio 1
	s_barrier
	s_waitcnt lgkmcnt(7)
	v_mfma_f32_16x16x32_f16 v[128:131], v[138:141], v[170:173], v[128:131]
	v_mfma_f32_16x16x32_f16 v[124:127], v[146:149], v[170:173], v[124:127]
	s_waitcnt lgkmcnt(5)
	v_mfma_f32_16x16x32_f16 v[112:115], v[138:141], v[178:181], v[112:115]
	v_mfma_f32_16x16x32_f16 v[108:111], v[146:149], v[178:181], v[108:111]
	s_waitcnt lgkmcnt(3)
	v_mfma_f32_16x16x32_f16 v[96:99], v[138:141], v[198:201], v[96:99]
	v_mfma_f32_16x16x32_f16 v[92:95], v[146:149], v[198:201], v[92:95]
	s_waitcnt lgkmcnt(1)
	v_mfma_f32_16x16x32_f16 v[80:83], v[138:141], v[208:211], v[80:83]
	v_mfma_f32_16x16x32_f16 v[76:79], v[146:149], v[208:211], v[76:79]
	v_mfma_f32_16x16x32_f16 v[128:131], v[142:145], v[174:177], v[128:131]
	v_mfma_f32_16x16x32_f16 v[124:127], v[150:153], v[174:177], v[124:127]
	v_mfma_f32_16x16x32_f16 v[112:115], v[142:145], v[190:193], v[112:115]
	v_mfma_f32_16x16x32_f16 v[108:111], v[150:153], v[190:193], v[108:111]
	v_mfma_f32_16x16x32_f16 v[96:99], v[142:145], v[204:207], v[96:99]
	v_mfma_f32_16x16x32_f16 v[92:95], v[150:153], v[204:207], v[92:95]
	s_waitcnt lgkmcnt(0)
	v_mfma_f32_16x16x32_f16 v[80:83], v[142:145], v[212:215], v[80:83]
	v_mfma_f32_16x16x32_f16 v[76:79], v[150:153], v[212:215], v[76:79]
	v_mfma_f32_16x16x32_f16 v[120:123], v[154:157], v[170:173], v[120:123]
	v_mfma_f32_16x16x32_f16 v[116:119], v[162:165], v[170:173], v[116:119]
	v_mfma_f32_16x16x32_f16 v[104:107], v[154:157], v[178:181], v[104:107]
	v_mfma_f32_16x16x32_f16 v[100:103], v[162:165], v[178:181], v[100:103]
	v_mfma_f32_16x16x32_f16 v[88:91], v[154:157], v[198:201], v[88:91]
	v_mfma_f32_16x16x32_f16 v[84:87], v[162:165], v[198:201], v[84:87]
	v_mfma_f32_16x16x32_f16 v[72:75], v[154:157], v[208:211], v[72:75]
	v_mfma_f32_16x16x32_f16 v[68:71], v[162:165], v[208:211], v[68:71]
	v_mfma_f32_16x16x32_f16 v[120:123], v[158:161], v[174:177], v[120:123]
	v_mfma_f32_16x16x32_f16 v[116:119], v[166:169], v[174:177], v[116:119]
	v_mfma_f32_16x16x32_f16 v[104:107], v[158:161], v[190:193], v[104:107]
	v_mfma_f32_16x16x32_f16 v[100:103], v[166:169], v[190:193], v[100:103]
	v_mfma_f32_16x16x32_f16 v[88:91], v[158:161], v[204:207], v[88:91]
	v_mfma_f32_16x16x32_f16 v[84:87], v[166:169], v[204:207], v[84:87]
	v_mfma_f32_16x16x32_f16 v[72:75], v[158:161], v[212:215], v[72:75]
	v_mfma_f32_16x16x32_f16 v[68:71], v[166:169], v[212:215], v[68:71]
	s_barrier
; #define PG8_STAGE(bufoff, gbase, voff, h64) do { \
;         __builtin_amdgcn_global_load_lds((const unsigned*)((const char*)(gbase) + (voff)), (LAS unsigned*)(lds + (bufoff) + ldsw), 16, 0, 0); \
;         __builtin_amdgcn_global_load_lds((const unsigned*)((const char*)(gbase) + (h64) + (voff)), (LAS unsigned*)(lds + (bufoff) + ldsw + 8192), 16, 0, 0); } while (0)
; #define PG8_LDA(dst, b, h) do { _Pragma("unroll") for (int m = 0; m < 4; ++m) { dst[m].lo = *(const LAS f16x8*)(lds + PG8_SA(b, h) + aoff + m * 2048); dst[m].hi = *(const LAS f16x8*)(lds + PG8_SA(b, h) + aoff + m * 2048 + 1024); } } while (0)
; #define PG8_WAIT_V(n) asm volatile("s_waitcnt vmcnt(" #n ")" ::: "memory")
; #define PG8_WAIT_L(n) asm volatile("s_waitcnt lgkmcnt(" #n ")" ::: "memory")
; #define PG8_BAR __builtin_amdgcn_s_barrier()
; #define PG8_SCHED __builtin_amdgcn_sched_barrier(0)
; template <bool F8 = false, class Sched, class Epi>
; __device__ __forceinline__ void gemm_phase(LAS unsigned char* lds, const Sched& S, const Epi& E) {
;     ...
;         for (int t = 0; t < nt; t += 2) {
;     ...
;             PG8_LDA(At, 1, 1); PG8_STAGE(PG8_SB(1, 0), b3, vB2, h2); PG8_STAGE(PG8_SB(1, 1), b3 + bhs2, vB2, h2); PG8_STAGE(PG8_SA(1, 0), a3, vA2, h2);
;             PG8_WAIT_V(8); PG8_WAIT_L(0); PG8_BAR; PG8_MMA(1, 0, At, B0); PG8_MMA(1, 1, At, B1); PG8_BAR; PG8_SCHED;
	s_setprio 0
	s_add_i32 s6, s8, s49
	v_lshl_add_u64 v[136:137], v[182:183], 0, s[40:41]
	s_mov_b32 m0, s6
	ds_read_b128 v[170:173], v202 offset:49152
	ds_read_b128 v[174:177], v202 offset:50176
	ds_read_b128 v[178:181], v202 offset:51200
	ds_read_b128 v[190:193], v202 offset:52224
	ds_read_b128 v[198:201], v202 offset:53248
	ds_read_b128 v[204:207], v202 offset:54272
	ds_read_b128 v[208:211], v202 offset:55296
	ds_read_b128 v[212:215], v202 offset:56320
	global_load_lds_dwordx4 v[136:137], off
	v_lshl_add_u64 v[136:137], v[194:195], 0, s[40:41]
	s_add_i32 m0, s6, 0x2000
	s_add_i32 s6, s9, s49
	global_load_lds_dwordx4 v[136:137], off
	v_lshl_add_u64 v[136:137], v[216:217], 0, s[40:41]
	s_mov_b32 m0, s6
	s_nop 0
	global_load_lds_dwordx4 v[136:137], off
	v_lshl_add_u64 v[136:137], v[234:235], 0, s[40:41]
	s_add_i32 m0, s6, 0x2000
	s_nop 0
	global_load_lds_dwordx4 v[136:137], off
	v_lshl_add_u64 v[136:137], v[236:237], 0, s[40:41]
	s_mov_b32 m0, s92
	s_nop 0
	global_load_lds_dwordx4 v[136:137], off
	v_lshl_add_u64 v[136:137], v[238:239], 0, s[40:41]
	s_mov_b32 m0, s93
	s_nop 0
	global_load_lds_dwordx4 v[136:137], off
	s_waitcnt vmcnt(8)
	s_nop 0
	s_setprio 1
	s_barrier
	s_waitcnt lgkmcnt(7)
	v_mfma_f32_16x16x32_f16 v[64:67], v[138:141], v[170:173], v[64:67]
	v_mfma_f32_16x16x32_f16 v[60:63], v[146:149], v[170:173], v[60:63]
	s_waitcnt lgkmcnt(5)
	v_mfma_f32_16x16x32_f16 v[48:51], v[138:141], v[178:181], v[48:51]
	v_mfma_f32_16x16x32_f16 v[44:47], v[146:149], v[178:181], v[44:47]
	s_waitcnt lgkmcnt(3)
	v_mfma_f32_16x16x32_f16 v[28:31], v[138:141], v[198:201], v[28:31]
	v_mfma_f32_16x16x32_f16 v[24:27], v[146:149], v[198:201], v[24:27]
	s_waitcnt lgkmcnt(1)
	v_mfma_f32_16x16x32_f16 v[12:15], v[138:141], v[208:211], v[12:15]
	v_mfma_f32_16x16x32_f16 v[8:11], v[146:149], v[208:211], v[8:11]
	v_mfma_f32_16x16x32_f16 v[64:67], v[142:145], v[174:177], v[64:67]
	v_mfma_f32_16x16x32_f16 v[60:63], v[150:153], v[174:177], v[60:63]
	v_mfma_f32_16x16x32_f16 v[48:51], v[142:145], v[190:193], v[48:51]
	v_mfma_f32_16x16x32_f16 v[44:47], v[150:153], v[190:193], v[44:47]
	v_mfma_f32_16x16x32_f16 v[28:31], v[142:145], v[204:207], v[28:31]
	v_mfma_f32_16x16x32_f16 v[24:27], v[150:153], v[204:207], v[24:27]
	s_waitcnt lgkmcnt(0)
	v_mfma_f32_16x16x32_f16 v[12:15], v[142:145], v[212:215], v[12:15]
	v_mfma_f32_16x16x32_f16 v[8:11], v[150:153], v[212:215], v[8:11]
	v_mfma_f32_16x16x32_f16 v[56:59], v[154:157], v[170:173], v[56:59]
	v_mfma_f32_16x16x32_f16 v[52:55], v[162:165], v[170:173], v[52:55]
	v_mfma_f32_16x16x32_f16 v[40:43], v[154:157], v[178:181], v[40:43]
	v_mfma_f32_16x16x32_f16 v[36:39], v[162:165], v[178:181], v[36:39]
	v_mfma_f32_16x16x32_f16 v[20:23], v[154:157], v[198:201], v[20:23]
	v_mfma_f32_16x16x32_f16 v[16:19], v[162:165], v[198:201], v[16:19]
	v_mfma_f32_16x16x32_f16 v[4:7], v[154:157], v[208:211], v[4:7]
	v_mfma_f32_16x16x32_f16 v[0:3], v[162:165], v[208:211], v[0:3]
	v_mfma_f32_16x16x32_f16 v[56:59], v[158:161], v[174:177], v[56:59]
	v_mfma_f32_16x16x32_f16 v[52:55], v[166:169], v[174:177], v[52:55]
	v_mfma_f32_16x16x32_f16 v[40:43], v[158:161], v[190:193], v[40:43]
	v_mfma_f32_16x16x32_f16 v[36:39], v[166:169], v[190:193], v[36:39]
	v_mfma_f32_16x16x32_f16 v[20:23], v[158:161], v[204:207], v[20:23]
	v_mfma_f32_16x16x32_f16 v[16:19], v[166:169], v[204:207], v[16:19]
	v_mfma_f32_16x16x32_f16 v[4:7], v[158:161], v[212:215], v[4:7]
	v_mfma_f32_16x16x32_f16 v[0:3], v[166:169], v[212:215], v[0:3]
	s_barrier
	s_setprio 0
	s_add_u32 s10, s10, 0x100
	s_addc_u32 s11, s11, 0
	s_cmp_ge_u32 s79, s36
	s_cbranch_scc1 .LBB0_217
